# rwkv_scan task map: the two row-half workgroups of a (batch, head, dir) share one XCD so the second reader of the loader streams hits L2
# baseline (speedup 1.0000x reference)
.LBB0_1652:
	s_or_b64 exec, exec, s[0:1]
	s_add_u32 s76, s52, 0x3e5000f0
	v_mov_b32_e32 v4, v189
	s_mov_b32 s66, s33
	s_addc_u32 s77, s53, 0
	s_cmpk_lg_i32 s54, 0x100
	s_cbranch_scc1 .Lrwmap_done
	s_and_b32 s0, s33, 7
	s_lshl_b32 s0, s0, 1
	s_bfe_u32 s1, s33, 0x10003
	s_or_b32 s0, s0, s1
	s_and_b32 s1, s33, 0xf0
	s_or_b32 s66, s0, s1
.Lrwmap_done:
	s_waitcnt lgkmcnt(0)
	s_barrier
	s_cmpk_gt_i32 s66, 0xff
	v_readfirstlane_b32 s0, v4
	s_movk_i32 s67, 0xff
	s_cbranch_scc1 .LBB0_1727
	s_add_u32 s2, s52, 0x3e500138
	v_mov_b32_e32 v41, 0
	s_addc_u32 s3, s53, 0
	global_load_dwordx2 v[42:43], v41, s[2:3] offset:16
	v_mov_b32_e32 v5, 0x3e500000
	global_load_dwordx2 v[44:45], v41, s[76:77]
	global_load_dwordx4 v[0:3], v5, s[52:53] offset:312
	s_add_u32 s68, s52, 0x3d900000
	v_lshrrev_b32_e32 v5, 3, v4
	s_addc_u32 s69, s53, 0
	s_ashr_i32 s0, s0, 6
	v_and_b32_e32 v5, 6, v5
	v_lshl_or_b32 v156, s0, 3, v5
	v_add_u32_e32 v5, 0xffffff00, v4
	v_ashrrev_i32_e32 v158, 4, v5
	s_movk_i32 s4, 0xe01f
	v_mov_b32_e32 v171, 0xff
	v_mov_b32_e32 v172, 0x20ff
	v_cmp_lt_i32_e64 s[40:41], s4, v158
	v_lshlrev_b32_e32 v166, 8, v158
	v_add_u32_e32 v5, 0x20e0, v158
	v_add_u32_e32 v6, 0x1fe0, v158
	v_cndmask_b32_e64 v7, v171, v172, s[40:41]
	s_movk_i32 s5, 0xff08
	v_cndmask_b32_e64 v173, v5, v6, s[40:41]
	v_sub_u32_e32 v174, v7, v5
	v_add_u32_e32 v6, 0, v166
	s_mov_b32 s4, 0xc200
	v_mul_lo_u32 v7, v158, s5
	v_and_b32_e32 v47, 15, v4
	v_add3_u32 v177, v6, v7, s4
	s_movk_i32 s4, 0xe00f
	v_lshlrev_b32_e32 v157, 4, v47
	v_add_u32_e32 v162, 16, v158
	v_mov_b32_e32 v178, 0xffffff10
	v_cmp_lt_i32_e64 s[42:43], s4, v158
	v_mov_b32_e32 v179, 0xef
	v_mov_b32_e32 v180, 0x20ef
	v_lshlrev_b32_e32 v168, 8, v162
	v_add_u32_e32 v175, v6, v157
	v_cndmask_b32_e64 v6, 16, v178, s[42:43]
	v_cndmask_b32_e64 v8, v179, v180, s[42:43]
	v_add_u32_e32 v181, v6, v5
	v_sub_u32_e32 v182, v8, v5
	v_add_u32_e32 v5, 0, v168
	s_mov_b32 s4, 0xb280
	s_cmp_lt_i32 s0, 4
	s_movk_i32 s70, 0xef
	v_add_u32_e32 v183, v5, v157
	v_add3_u32 v185, v7, v5, s4
	s_movk_i32 s4, 0x211f
	s_cselect_b64 s[78:79], -1, 0
	v_lshlrev_b32_e32 v46, 2, v47
	v_cmp_lt_i32_e64 s[0:1], s67, v158
	v_add_u32_e32 v159, 0xffffff00, v158
	v_sub_u32_e32 v160, 0x20ff, v158
	v_sub_u32_e32 v161, 0xff, v158
	v_cmp_lt_i32_e64 s[2:3], s70, v158
	v_add_u32_e32 v163, 0xffffff10, v158
	v_sub_u32_e32 v164, 0x20ef, v158
	v_sub_u32_e32 v165, 0xef, v158
	s_mov_b32 s81, 0
	v_cmp_eq_u32_e64 s[6:7], 0, v47
	v_lshlrev_b32_e32 v167, 3, v158
	v_lshlrev_b32_e32 v169, 3, v162
	v_add_u32_e32 v170, 64, v158
	v_cmp_eq_u32_e64 s[8:9], 1, v47
	v_cmp_eq_u32_e64 s[10:11], 2, v47
	v_cmp_eq_u32_e64 s[12:13], 3, v47
	v_cmp_eq_u32_e64 s[14:15], 4, v47
	v_cmp_eq_u32_e64 s[16:17], 5, v47
	v_cmp_eq_u32_e64 s[18:19], 6, v47
	v_cmp_eq_u32_e64 s[20:21], 7, v47
	v_cmp_eq_u32_e64 s[22:23], 8, v47
	v_cmp_eq_u32_e64 s[24:25], 9, v47
	v_cmp_eq_u32_e64 s[26:27], 10, v47
	v_cmp_eq_u32_e64 s[28:29], 11, v47
	v_cmp_eq_u32_e64 s[30:31], 12, v47
	v_cmp_eq_u32_e64 s[34:35], 13, v47
	v_cmp_eq_u32_e64 s[36:37], 14, v47
	v_cmp_eq_u32_e64 s[38:39], 15, v47
	v_add_u32_e32 v176, 0xc200, v175
	v_add_u32_e32 v184, 0xc200, v183
	v_bitop3_b32 v186, v4, s4, 15 bitop3:0x6c
	v_or_b32_e32 v187, 0xfffffee0, v47
	v_sub_u32_e32 v188, 0, v158
	s_movk_i32 s71, 0x3000
	s_movk_i32 s84, 0x1fff
	s_mov_b64 s[82:83], 0x1000
	s_mov_b32 s85, 1.0
	s_mov_b32 s96, 0xf800000
	v_mov_b32_e32 v191, 0x260
	s_movk_i32 s97, 0xffe0
	v_mov_b32_e32 v49, -1.0
	v_mov_b32_e32 v51, 1.0
	v_mov_b32_e32 v192, 0x1fff
	s_branch .LBB0_1656
